# MLA loop: barrier-phased schedule with the plain softmax phase (exps into 32 registers, then sums and packs) instead of the rolling-temporary immediate-pack form
# speedup vs baseline: 1.0010x; 1.0007x over previous
.Lmv_pre_top:
	v_exp_f32_e32 v98, v66
	v_exp_f32_e32 v138, v50
	v_exp_f32_e32 v99, v67
	v_exp_f32_e32 v139, v51
	v_exp_f32_e32 v100, v68
	v_add_f32_e32 v155, v98, v99
	v_exp_f32_e32 v140, v52
	v_add_f32_e32 v156, v138, v139
	v_exp_f32_e32 v101, v69
	v_add_f32_e32 v155, v100, v155
	v_exp_f32_e32 v141, v53
	v_add_f32_e32 v156, v140, v156
	v_exp_f32_e32 v102, v70
	v_add_f32_e32 v155, v101, v155
	v_exp_f32_e32 v142, v54
	v_add_f32_e32 v156, v141, v156
	v_exp_f32_e32 v103, v71
	v_add_f32_e32 v155, v102, v155
	v_exp_f32_e32 v143, v55
	v_add_f32_e32 v156, v142, v156
	v_exp_f32_e32 v104, v72
	v_add_f32_e32 v155, v103, v155
	v_exp_f32_e32 v144, v56
	v_add_f32_e32 v156, v143, v156
	v_exp_f32_e32 v105, v73
	v_add_f32_e32 v155, v104, v155
	v_exp_f32_e32 v145, v57
	v_add_f32_e32 v156, v144, v156
	v_exp_f32_e32 v106, v74
	v_add_f32_e32 v155, v105, v155
	v_exp_f32_e32 v146, v58
	v_add_f32_e32 v156, v145, v156
	v_exp_f32_e32 v107, v75
	v_add_f32_e32 v155, v106, v155
	v_exp_f32_e32 v147, v59
	v_add_f32_e32 v156, v146, v156
	v_exp_f32_e32 v108, v76
	v_add_f32_e32 v155, v107, v155
	v_exp_f32_e32 v148, v60
	v_add_f32_e32 v156, v147, v156
	v_exp_f32_e32 v109, v77
	v_add_f32_e32 v155, v108, v155
	v_exp_f32_e32 v149, v61
	v_add_f32_e32 v156, v148, v156
	v_exp_f32_e32 v110, v78
	v_add_f32_e32 v155, v109, v155
	v_exp_f32_e32 v150, v62
	v_add_f32_e32 v156, v149, v156
	v_exp_f32_e32 v111, v79
	v_add_f32_e32 v155, v110, v155
	v_exp_f32_e32 v151, v63
	v_add_f32_e32 v156, v150, v156
	v_exp_f32_e32 v112, v80
	v_add_f32_e32 v155, v111, v155
	v_exp_f32_e32 v152, v64
	v_add_f32_e32 v156, v151, v156
	v_exp_f32_e32 v113, v81
	v_add_f32_e32 v155, v112, v155
	v_exp_f32_e32 v153, v65
	v_add_f32_e32 v156, v152, v156
	v_add_f32_e32 v155, v113, v155
	v_add_f32_e32 v156, v153, v156
	v_add_f32_e32 v157, v155, v156
	s_nop 0
	v_cmp_ngt_f32_e32 vcc, s72, v157
	s_nop 1
	s_or_b64 vcc, vcc, s[4:5]
	s_andn2_b64 vcc, vcc, s[10:11]
	s_cbranch_vccz .Lmv_pre_fast
	v_max3_f32 v154, v66, v67, v68
	v_max3_f32 v154, v154, v69, v70
	v_max3_f32 v154, v154, v71, v72
	v_max3_f32 v154, v154, v73, v74
	v_max3_f32 v154, v154, v75, v76
	v_max3_f32 v154, v154, v77, v78
	v_max3_f32 v154, v154, v79, v80
	v_max3_f32 v154, v154, v81, v50
	v_max3_f32 v154, v154, v51, v52
	v_max3_f32 v154, v154, v53, v54
	v_max3_f32 v154, v154, v55, v56
	v_max3_f32 v154, v154, v57, v58
	v_max3_f32 v154, v154, v59, v60
	v_max3_f32 v154, v154, v61, v62
	v_max3_f32 v154, v154, v63, v64
	v_max_f32_e32 v154, v154, v65
	ds_bpermute_b32 v148, v195, v154
	s_waitcnt lgkmcnt(0)
	v_max_f32_e32 v154, v154, v148
	s_and_b64 vcc, exec, s[4:5]
	s_cbranch_vccnz .Lmv_pre_anchor
	v_max_f32_e32 v154, 0, v154
	v_exp_f32_e64 v149, -v154
	s_nop 7
	s_nop 7
	v_mul_f32_e32 v183, v183, v149
	v_mul_f32_e32 v2, v2, v149
	v_mul_f32_e32 v3, v3, v149
	v_mul_f32_e32 v4, v4, v149
	v_mul_f32_e32 v5, v5, v149
	v_mul_f32_e32 v6, v6, v149
	v_mul_f32_e32 v7, v7, v149
	v_mul_f32_e32 v8, v8, v149
	v_mul_f32_e32 v9, v9, v149
	v_mul_f32_e32 v10, v10, v149
	v_mul_f32_e32 v11, v11, v149
	v_mul_f32_e32 v12, v12, v149
	v_mul_f32_e32 v13, v13, v149
	v_mul_f32_e32 v14, v14, v149
	v_mul_f32_e32 v15, v15, v149
	v_mul_f32_e32 v16, v16, v149
	v_mul_f32_e32 v17, v17, v149
	v_mul_f32_e32 v18, v18, v149
	v_mul_f32_e32 v19, v19, v149
	v_mul_f32_e32 v20, v20, v149
	v_mul_f32_e32 v21, v21, v149
	v_mul_f32_e32 v22, v22, v149
	v_mul_f32_e32 v23, v23, v149
	v_mul_f32_e32 v24, v24, v149
	v_mul_f32_e32 v25, v25, v149
	v_mul_f32_e32 v26, v26, v149
	v_mul_f32_e32 v27, v27, v149
	v_mul_f32_e32 v28, v28, v149
	v_mul_f32_e32 v29, v29, v149
	v_mul_f32_e32 v30, v30, v149
	v_mul_f32_e32 v31, v31, v149
	v_mul_f32_e32 v32, v32, v149
	v_mul_f32_e32 v33, v33, v149

.Lmv_pre_fast:
	v_cvt_pk_bf16_f32 v82, v98, v99
	v_cvt_pk_bf16_f32 v83, v100, v101
	v_cvt_pk_bf16_f32 v84, v102, v103
	v_cvt_pk_bf16_f32 v85, v104, v105
	v_cvt_pk_bf16_f32 v86, v106, v107
	v_cvt_pk_bf16_f32 v87, v108, v109
	v_cvt_pk_bf16_f32 v88, v110, v111
	v_cvt_pk_bf16_f32 v89, v112, v113
	v_cvt_pk_bf16_f32 v90, v138, v139
	v_cvt_pk_bf16_f32 v91, v140, v141
	v_cvt_pk_bf16_f32 v92, v142, v143
	v_cvt_pk_bf16_f32 v93, v144, v145
	v_cvt_pk_bf16_f32 v94, v146, v147
	v_cvt_pk_bf16_f32 v95, v148, v149
	v_cvt_pk_bf16_f32 v96, v150, v151
	v_cvt_pk_bf16_f32 v97, v152, v153
	v_add_f32_e32 v183, v183, v157

.Lmv_h1a_fast:
	v_cvt_pk_bf16_f32 v82, v98, v99
	v_cvt_pk_bf16_f32 v83, v100, v101
	v_cvt_pk_bf16_f32 v84, v102, v103
	v_cvt_pk_bf16_f32 v85, v104, v105
	v_cvt_pk_bf16_f32 v86, v106, v107
	v_cvt_pk_bf16_f32 v87, v108, v109
	v_cvt_pk_bf16_f32 v88, v110, v111
	v_cvt_pk_bf16_f32 v89, v112, v113
	v_cvt_pk_bf16_f32 v90, v138, v139
	v_cvt_pk_bf16_f32 v91, v140, v141
	v_cvt_pk_bf16_f32 v92, v142, v143
	v_cvt_pk_bf16_f32 v93, v144, v145
	v_cvt_pk_bf16_f32 v94, v146, v147
	v_cvt_pk_bf16_f32 v95, v148, v149
	v_cvt_pk_bf16_f32 v96, v150, v151
	v_cvt_pk_bf16_f32 v97, v152, v153
	v_add_f32_e32 v183, v183, v157
	v_lshl_add_u32 v0, s12, 14, v159
	s_add_i32 s0, s35, 0xffffc000
	s_and_b32 s0, s0, 0x4000
	v_add_u32_e32 v154, s0, v190
	v_add_u32_e32 v210, v0, v184
	v_add_u32_e32 v211, v0, v185
	v_add_u32_e32 v212, v0, v186
	v_add_u32_e32 v213, v0, v187
	v_add_u32_e32 v214, v0, v188
	v_add_u32_e32 v215, v0, v189
	v_add_u32_e32 v216, v154, v191
	v_add_u32_e32 v217, v154, v192
	v_add_u32_e32 v196, v154, v193
	v_add_u32_e32 v197, v154, v194
	ds_read_b128 v[98:101], v210
	ds_read_b128 v[102:105], v210 offset:8192
	ds_read_b128 v[106:109], v211
	ds_read_b128 v[110:113], v211 offset:8192
	s_barrier
	s_setprio 1
	s_waitcnt lgkmcnt(3)
	v_mfma_f32_32x32x16_bf16 v[66:81], v[98:101], v[114:117], v[34:49]
	ds_read_b128 v[98:101], v212
	s_waitcnt lgkmcnt(3)
	v_mfma_f32_32x32x16_bf16 v[50:65], v[102:105], v[114:117], v[34:49]
	ds_read_b128 v[102:105], v212 offset:8192
	s_waitcnt lgkmcnt(3)
	v_mfma_f32_32x32x16_bf16 v[66:81], v[106:109], v[118:121], v[66:81]
	ds_read_b128 v[106:109], v213
	s_waitcnt lgkmcnt(3)
	v_mfma_f32_32x32x16_bf16 v[50:65], v[110:113], v[118:121], v[50:65]
	ds_read_b128 v[110:113], v213 offset:8192
	s_waitcnt lgkmcnt(3)
	v_mfma_f32_32x32x16_bf16 v[66:81], v[98:101], v[122:125], v[66:81]
	ds_read_b128 v[98:101], v214
	s_waitcnt lgkmcnt(3)
	v_mfma_f32_32x32x16_bf16 v[50:65], v[102:105], v[122:125], v[50:65]
	ds_read_b128 v[102:105], v214 offset:8192
	s_waitcnt lgkmcnt(3)
	v_mfma_f32_32x32x16_bf16 v[66:81], v[106:109], v[126:129], v[66:81]
	ds_read_b128 v[106:109], v215
	s_waitcnt lgkmcnt(3)
	v_mfma_f32_32x32x16_bf16 v[50:65], v[110:113], v[126:129], v[50:65]
	ds_read_b128 v[110:113], v215 offset:8192
	s_waitcnt lgkmcnt(3)
	v_mfma_f32_32x32x16_bf16 v[66:81], v[98:101], v[130:133], v[66:81]
	ds_read_b128 v[98:101], v216
	s_waitcnt lgkmcnt(3)
	v_mfma_f32_32x32x16_bf16 v[50:65], v[102:105], v[130:133], v[50:65]
	ds_read_b128 v[102:105], v216 offset:4096
	s_waitcnt lgkmcnt(3)
	v_mfma_f32_32x32x16_bf16 v[66:81], v[106:109], v[134:137], v[66:81]
	ds_read_b128 v[106:109], v217
	s_waitcnt lgkmcnt(3)
	v_mfma_f32_32x32x16_bf16 v[50:65], v[110:113], v[134:137], v[50:65]
	ds_read_b128 v[110:113], v217 offset:4096
	s_waitcnt lgkmcnt(3)
	v_mfma_f32_32x32x16_bf16 v[2:17], v[98:101], v[82:85], v[2:17]
	ds_read_b128 v[98:101], v196
	s_waitcnt lgkmcnt(3)
	v_mfma_f32_32x32x16_bf16 v[18:33], v[102:105], v[82:85], v[18:33]
	ds_read_b128 v[102:105], v196 offset:4096
	s_waitcnt lgkmcnt(3)
	v_mfma_f32_32x32x16_bf16 v[2:17], v[106:109], v[86:89], v[2:17]
	ds_read_b128 v[106:109], v197
	s_waitcnt lgkmcnt(3)
	v_mfma_f32_32x32x16_bf16 v[18:33], v[110:113], v[86:89], v[18:33]
	ds_read_b128 v[110:113], v197 offset:4096
	s_waitcnt lgkmcnt(3)
	v_mfma_f32_32x32x16_bf16 v[2:17], v[98:101], v[90:93], v[2:17]
	s_waitcnt lgkmcnt(2)
	v_mfma_f32_32x32x16_bf16 v[18:33], v[102:105], v[90:93], v[18:33]
	s_waitcnt lgkmcnt(1)
	v_mfma_f32_32x32x16_bf16 v[2:17], v[106:109], v[94:97], v[2:17]
	s_waitcnt lgkmcnt(0)
	v_mfma_f32_32x32x16_bf16 v[18:33], v[110:113], v[94:97], v[18:33]
	s_setprio 0
	s_barrier
	s_cmp_ge_u32 s36, s34
	s_cbranch_scc1 .Lmv1_skip1
	s_and_b32 s0, s35, 0x4000
	s_add_i32 m0, s27, s0
	v_lshl_add_u64 v[198:199], s[84:85], 0, v[176:177]
	v_lshl_add_u64 v[198:199], v[198:199], 0, s[78:79]
	global_load_lds_dwordx4 v[198:199], off

.Lmv_h1b_fast:
	v_cvt_pk_bf16_f32 v82, v98, v99
	v_cvt_pk_bf16_f32 v83, v100, v101
	v_cvt_pk_bf16_f32 v84, v102, v103
	v_cvt_pk_bf16_f32 v85, v104, v105
	v_cvt_pk_bf16_f32 v86, v106, v107
	v_cvt_pk_bf16_f32 v87, v108, v109
	v_cvt_pk_bf16_f32 v88, v110, v111
	v_cvt_pk_bf16_f32 v89, v112, v113
	v_cvt_pk_bf16_f32 v90, v138, v139
	v_cvt_pk_bf16_f32 v91, v140, v141
	v_cvt_pk_bf16_f32 v92, v142, v143
	v_cvt_pk_bf16_f32 v93, v144, v145
	v_cvt_pk_bf16_f32 v94, v146, v147
	v_cvt_pk_bf16_f32 v95, v148, v149
	v_cvt_pk_bf16_f32 v96, v150, v151
	v_cvt_pk_bf16_f32 v97, v152, v153
	v_add_f32_e32 v183, v183, v157
	s_add_i32 s8, s8, 0x8000
	s_and_b32 s0, s8, 0x8000
	v_add_u32_e32 v0, s0, v159
	v_lshl_add_u32 v154, s12, 13, v190
	v_add_u32_e32 v210, v0, v184
	v_add_u32_e32 v211, v0, v185
	v_add_u32_e32 v212, v0, v186
	v_add_u32_e32 v213, v0, v187
	v_add_u32_e32 v214, v0, v188
	v_add_u32_e32 v215, v0, v189
	v_add_u32_e32 v216, v154, v191
	v_add_u32_e32 v217, v154, v192
	v_add_u32_e32 v196, v154, v193
	v_add_u32_e32 v197, v154, v194
	ds_read_b128 v[98:101], v210
	ds_read_b128 v[102:105], v210 offset:8192
	ds_read_b128 v[106:109], v211
	ds_read_b128 v[110:113], v211 offset:8192
	s_barrier
	s_setprio 1
	s_waitcnt lgkmcnt(3)
	v_mfma_f32_32x32x16_bf16 v[66:81], v[98:101], v[114:117], v[34:49]
	ds_read_b128 v[98:101], v212
	s_waitcnt lgkmcnt(3)
	v_mfma_f32_32x32x16_bf16 v[50:65], v[102:105], v[114:117], v[34:49]
	ds_read_b128 v[102:105], v212 offset:8192
	s_waitcnt lgkmcnt(3)
	v_mfma_f32_32x32x16_bf16 v[66:81], v[106:109], v[118:121], v[66:81]
	ds_read_b128 v[106:109], v213
	s_waitcnt lgkmcnt(3)
	v_mfma_f32_32x32x16_bf16 v[50:65], v[110:113], v[118:121], v[50:65]
	ds_read_b128 v[110:113], v213 offset:8192
	s_waitcnt lgkmcnt(3)
	v_mfma_f32_32x32x16_bf16 v[66:81], v[98:101], v[122:125], v[66:81]
	ds_read_b128 v[98:101], v214
	s_waitcnt lgkmcnt(3)
	v_mfma_f32_32x32x16_bf16 v[50:65], v[102:105], v[122:125], v[50:65]
	ds_read_b128 v[102:105], v214 offset:8192
	s_waitcnt lgkmcnt(3)
	v_mfma_f32_32x32x16_bf16 v[66:81], v[106:109], v[126:129], v[66:81]
	ds_read_b128 v[106:109], v215
	s_waitcnt lgkmcnt(3)
	v_mfma_f32_32x32x16_bf16 v[50:65], v[110:113], v[126:129], v[50:65]
	ds_read_b128 v[110:113], v215 offset:8192
	s_waitcnt lgkmcnt(3)
	v_mfma_f32_32x32x16_bf16 v[66:81], v[98:101], v[130:133], v[66:81]
	ds_read_b128 v[98:101], v216
	s_waitcnt lgkmcnt(3)
	v_mfma_f32_32x32x16_bf16 v[50:65], v[102:105], v[130:133], v[50:65]
	ds_read_b128 v[102:105], v216 offset:4096
	s_waitcnt lgkmcnt(3)
	v_mfma_f32_32x32x16_bf16 v[66:81], v[106:109], v[134:137], v[66:81]
	ds_read_b128 v[106:109], v217
	s_waitcnt lgkmcnt(3)
	v_mfma_f32_32x32x16_bf16 v[50:65], v[110:113], v[134:137], v[50:65]
	ds_read_b128 v[110:113], v217 offset:4096
	s_waitcnt lgkmcnt(3)
	v_mfma_f32_32x32x16_bf16 v[2:17], v[98:101], v[82:85], v[2:17]
	ds_read_b128 v[98:101], v196
	s_waitcnt lgkmcnt(3)
	v_mfma_f32_32x32x16_bf16 v[18:33], v[102:105], v[82:85], v[18:33]
	ds_read_b128 v[102:105], v196 offset:4096
	s_waitcnt lgkmcnt(3)
	v_mfma_f32_32x32x16_bf16 v[2:17], v[106:109], v[86:89], v[2:17]
	ds_read_b128 v[106:109], v197
	s_waitcnt lgkmcnt(3)
	v_mfma_f32_32x32x16_bf16 v[18:33], v[110:113], v[86:89], v[18:33]
	ds_read_b128 v[110:113], v197 offset:4096
	s_waitcnt lgkmcnt(3)
	v_mfma_f32_32x32x16_bf16 v[2:17], v[98:101], v[90:93], v[2:17]
	s_waitcnt lgkmcnt(2)
	v_mfma_f32_32x32x16_bf16 v[18:33], v[102:105], v[90:93], v[18:33]
	s_waitcnt lgkmcnt(1)
	v_mfma_f32_32x32x16_bf16 v[2:17], v[106:109], v[94:97], v[2:17]
	s_waitcnt lgkmcnt(0)
	v_mfma_f32_32x32x16_bf16 v[18:33], v[110:113], v[94:97], v[18:33]
	s_setprio 0
	s_branch .Lmjoin

.Lmv_h0a_fast:
	v_cvt_pk_bf16_f32 v82, v98, v99
	v_cvt_pk_bf16_f32 v83, v100, v101
	v_cvt_pk_bf16_f32 v84, v102, v103
	v_cvt_pk_bf16_f32 v85, v104, v105
	v_cvt_pk_bf16_f32 v86, v106, v107
	v_cvt_pk_bf16_f32 v87, v108, v109
	v_cvt_pk_bf16_f32 v88, v110, v111
	v_cvt_pk_bf16_f32 v89, v112, v113
	v_cvt_pk_bf16_f32 v90, v138, v139
	v_cvt_pk_bf16_f32 v91, v140, v141
	v_cvt_pk_bf16_f32 v92, v142, v143
	v_cvt_pk_bf16_f32 v93, v144, v145
	v_cvt_pk_bf16_f32 v94, v146, v147
	v_cvt_pk_bf16_f32 v95, v148, v149
	v_cvt_pk_bf16_f32 v96, v150, v151
	v_cvt_pk_bf16_f32 v97, v152, v153
	v_add_f32_e32 v183, v183, v157
	s_add_i32 s8, s8, 0x8000
	s_and_b32 s0, s8, 0x8000
	v_add_u32_e32 v0, s0, v159
	v_lshl_add_u32 v154, s12, 13, v190
	v_add_u32_e32 v210, v0, v184
	v_add_u32_e32 v211, v0, v185
	v_add_u32_e32 v212, v0, v186
	v_add_u32_e32 v213, v0, v187
	v_add_u32_e32 v214, v0, v188
	v_add_u32_e32 v215, v0, v189
	v_add_u32_e32 v216, v154, v191
	v_add_u32_e32 v217, v154, v192
	v_add_u32_e32 v196, v154, v193
	v_add_u32_e32 v197, v154, v194
	ds_read_b128 v[98:101], v210
	ds_read_b128 v[102:105], v210 offset:8192
	ds_read_b128 v[106:109], v211
	ds_read_b128 v[110:113], v211 offset:8192
	s_barrier
	s_setprio 1
	s_waitcnt lgkmcnt(3)
	v_mfma_f32_32x32x16_bf16 v[66:81], v[98:101], v[114:117], v[34:49]
	ds_read_b128 v[98:101], v212
	s_waitcnt lgkmcnt(3)
	v_mfma_f32_32x32x16_bf16 v[50:65], v[102:105], v[114:117], v[34:49]
	ds_read_b128 v[102:105], v212 offset:8192
	s_waitcnt lgkmcnt(3)
	v_mfma_f32_32x32x16_bf16 v[66:81], v[106:109], v[118:121], v[66:81]
	ds_read_b128 v[106:109], v213
	s_waitcnt lgkmcnt(3)
	v_mfma_f32_32x32x16_bf16 v[50:65], v[110:113], v[118:121], v[50:65]
	ds_read_b128 v[110:113], v213 offset:8192
	s_waitcnt lgkmcnt(3)
	v_mfma_f32_32x32x16_bf16 v[66:81], v[98:101], v[122:125], v[66:81]
	ds_read_b128 v[98:101], v214
	s_waitcnt lgkmcnt(3)
	v_mfma_f32_32x32x16_bf16 v[50:65], v[102:105], v[122:125], v[50:65]
	ds_read_b128 v[102:105], v214 offset:8192
	s_waitcnt lgkmcnt(3)
	v_mfma_f32_32x32x16_bf16 v[66:81], v[106:109], v[126:129], v[66:81]
	ds_read_b128 v[106:109], v215
	s_waitcnt lgkmcnt(3)
	v_mfma_f32_32x32x16_bf16 v[50:65], v[110:113], v[126:129], v[50:65]
	ds_read_b128 v[110:113], v215 offset:8192
	s_waitcnt lgkmcnt(3)
	v_mfma_f32_32x32x16_bf16 v[66:81], v[98:101], v[130:133], v[66:81]
	ds_read_b128 v[98:101], v216
	s_waitcnt lgkmcnt(3)
	v_mfma_f32_32x32x16_bf16 v[50:65], v[102:105], v[130:133], v[50:65]
	ds_read_b128 v[102:105], v216 offset:4096
	s_waitcnt lgkmcnt(3)
	v_mfma_f32_32x32x16_bf16 v[66:81], v[106:109], v[134:137], v[66:81]
	ds_read_b128 v[106:109], v217
	s_waitcnt lgkmcnt(3)
	v_mfma_f32_32x32x16_bf16 v[50:65], v[110:113], v[134:137], v[50:65]
	ds_read_b128 v[110:113], v217 offset:4096
	s_waitcnt lgkmcnt(3)
	v_mfma_f32_32x32x16_bf16 v[2:17], v[98:101], v[82:85], v[2:17]
	ds_read_b128 v[98:101], v196
	s_waitcnt lgkmcnt(3)
	v_mfma_f32_32x32x16_bf16 v[18:33], v[102:105], v[82:85], v[18:33]
	ds_read_b128 v[102:105], v196 offset:4096
	s_waitcnt lgkmcnt(3)
	v_mfma_f32_32x32x16_bf16 v[2:17], v[106:109], v[86:89], v[2:17]
	ds_read_b128 v[106:109], v197
	s_waitcnt lgkmcnt(3)
	v_mfma_f32_32x32x16_bf16 v[18:33], v[110:113], v[86:89], v[18:33]
	ds_read_b128 v[110:113], v197 offset:4096
	s_waitcnt lgkmcnt(3)
	v_mfma_f32_32x32x16_bf16 v[2:17], v[98:101], v[90:93], v[2:17]
	s_waitcnt lgkmcnt(2)
	v_mfma_f32_32x32x16_bf16 v[18:33], v[102:105], v[90:93], v[18:33]
	s_waitcnt lgkmcnt(1)
	v_mfma_f32_32x32x16_bf16 v[2:17], v[106:109], v[94:97], v[2:17]
	s_waitcnt lgkmcnt(0)
	v_mfma_f32_32x32x16_bf16 v[18:33], v[110:113], v[94:97], v[18:33]
	s_setprio 0
	s_barrier
	s_cmp_ge_u32 s36, s34
	s_cbranch_scc1 .Lmjoin
	s_mov_b64 s[4:5], 0
	s_mov_b64 s[10:11], 0
